# P8: non-temporal F stores for row tiles j >= 10 (instead of 12)
# speedup vs baseline: 1.0073x; 1.0023x over previous
.LBB0_898:
	s_mul_i32 s98, s26, 0xccd
	s_lshr_b32 s98, s98, 16
	s_mul_i32 s98, s98, 20
	s_sub_i32 s98, s26, s98
	s_cmp_ge_u32 s98, 10
	s_cselect_b32 s99, 1, 0
	v_max_f32_e32 v125, v125, v125
	v_max_f32_e32 v124, v124, v124
	v_max_f32_e32 v127, v127, v127
	v_max_f32_e32 v126, v126, v126
	v_max_f32_e32 v121, v121, v121
	v_max_f32_e32 v120, v120, v120
	v_max_f32_e32 v123, v123, v123
	v_max_f32_e32 v122, v122, v122
	v_max_f32_e32 v125, 0, v125
	v_max_f32_e32 v124, 0, v124
	v_max_f32_e32 v127, 0, v127
	v_max_f32_e32 v126, 0, v126
	v_max_f32_e32 v121, 0, v121
	v_max_f32_e32 v120, 0, v120
	v_max_f32_e32 v123, 0, v123
	v_max_f32_e32 v122, 0, v122
	v_pk_mul_f32 v[126:127], v[126:127], v[126:127]
	v_pk_mul_f32 v[124:125], v[124:125], v[124:125]
	v_pk_mul_f32 v[152:153], v[122:123], v[122:123]
	v_pk_mul_f32 v[122:123], v[120:121], v[120:121]
	s_nop 7
	v_cvt_pk_bf16_f32 v120, v124, v125
	v_cvt_pk_bf16_f32 v121, v126, v127
	v_cvt_pk_bf16_f32 v122, v122, v123
	v_cvt_pk_bf16_f32 v123, v152, v153
	v_max_f32_e32 v117, 0, v117
	v_max_f32_e32 v116, 0, v116
	v_max_f32_e32 v119, 0, v119
	v_max_f32_e32 v118, 0, v118
	v_max_f32_e32 v113, 0, v113
	v_max_f32_e32 v112, 0, v112
	v_max_f32_e32 v115, 0, v115
	v_max_f32_e32 v114, 0, v114
	ds_write_b128 v147, v[120:123]
	v_pk_mul_f32 v[118:119], v[118:119], v[118:119]
	v_pk_mul_f32 v[116:117], v[116:117], v[116:117]
	v_pk_mul_f32 v[120:121], v[114:115], v[114:115]
	v_pk_mul_f32 v[114:115], v[112:113], v[112:113]
	v_lshl_add_u32 v150, s26, 8, v143
	v_cvt_pk_bf16_f32 v112, v116, v117
	v_cvt_pk_bf16_f32 v113, v118, v119
	v_cvt_pk_bf16_f32 v114, v114, v115
	v_cvt_pk_bf16_f32 v115, v120, v121
	v_ashrrev_i32_e32 v151, 31, v150
	ds_write_b128 v147, v[112:115] offset:64
	v_lshlrev_b64 v[150:151], 13, v[150:151]
	s_lshl_b32 s28, s61, 8
	ds_read_b128 v[114:117], v148
	ds_read_b128 v[118:121], v148 offset:1152
	v_lshl_add_u64 v[150:151], s[4:5], 0, v[150:151]
	s_ashr_i32 s29, s28, 31
	v_lshl_add_u64 v[112:113], s[28:29], 1, v[150:151]
	v_lshl_add_u64 v[112:113], v[112:113], 0, s[8:9]
	v_lshl_add_u64 v[112:113], v[112:113], 0, v[132:133]
	s_waitcnt lgkmcnt(0)
	s_cmp_lg_u32 s99, 0
	s_cbranch_scc1 .Lf8nt_0
	global_store_dwordx4 v[112:113], v[114:117], off
	s_branch .Lf8d_0
